# first grid barrier (after the prologue) replaced by a flat counter barrier in the zeroed control area
# speedup vs baseline: 1.0289x; 1.0001x over previous
.LBB0_111:
	s_or_b64 exec, exec, s[4:5]
	v_readlane_b32 s4, v251, 3
	v_readlane_b32 s5, v251, 4
	s_cmp_eq_u32 s5, 1
	s_cbranch_scc1 .LBB0_123
	s_waitcnt vmcnt(0) lgkmcnt(0)
	s_barrier
	s_and_saveexec_b64 s[4:5], s[84:85]
	s_cbranch_execz .Lgsync_join
	buffer_wbl2 sc1
	s_waitcnt vmcnt(0)
	s_add_u32 s6, s33, 0x4b0
	s_addc_u32 s7, s49, 0
	v_mov_b32_e32 v2, 0
	v_mov_b32_e32 v5, 1
	global_atomic_add v2, v5, s[6:7]
.Lgsync_spin:
	s_sleep 1
	global_load_dword v5, v2, s[6:7] sc1
	s_waitcnt vmcnt(0)
	v_readfirstlane_b32 s8, v5
	s_nop 3
	s_cmp_lt_u32 s8, s94
	s_cbranch_scc1 .Lgsync_spin
	buffer_inv sc1
	s_waitcnt vmcnt(0)
